# phase 0 weight-transpose tiles: second batch of 4 row loads issued with the first batch (one load round trip per tile instead of two)
# speedup vs baseline: 1.0049x; 1.0049x over previous
; __device__ void phase_prep(const Params& p, unsigned char* smem) {
;     ...
;         const int k0 = (li / tn) * 64, n0 = (li % tn) * 64;
; #pragma unroll
;         for (int e = 0; e < 8; ++e) { const int idx = e * 512 + tid, kk = idx >> 6, nn = idx & 63, n = n0 + nn;
;             t[kk * 65 + nn] = (n < N) ? src[(size_t)(k0 + kk) * N + n] * scale : 0.f; }
.LBB0_46:
	s_or_saveexec_b64 s[24:25], s[22:23]
	v_ashrrev_i32_e32 v7, 31, v6
	s_lshl_b32 s22, s35, 6
	v_lshl_add_u64 v[6:7], v[6:7], 2, s[20:21]
	v_mov_b32_e32 v8, 0
	v_mov_b32_e32 v9, 0
	s_xor_b64 exec, exec, s[24:25]
	s_cbranch_execz .LBB0_48
	v_or_b32_e32 v4, s22, v1
	s_ashr_i32 s20, s22, 31
	s_mul_i32 s23, s20, s33
	v_mad_u64_u32 v[8:9], s[20:21], v4, s33, 0
	v_or_b32_e32 v4, s22, v10
	v_add_u32_e32 v9, s23, v9
	v_mad_u64_u32 v[26:27], s[20:21], v4, s33, 0
	v_lshl_add_u64 v[8:9], v[8:9], 2, v[6:7]
	v_add_u32_e32 v27, s23, v27
	v_lshl_add_u64 v[26:27], v[26:27], 2, v[6:7]
	global_load_dword v4, v[8:9], off
	global_load_dword v28, v[26:27], off
	v_or_b32_e32 v8, s22, v11
	v_mad_u64_u32 v[8:9], s[20:21], v8, s33, 0
	v_or_b32_e32 v26, s22, v12
	v_add_u32_e32 v9, s23, v9
	v_mad_u64_u32 v[26:27], s[20:21], v26, s33, 0
	v_lshl_add_u64 v[8:9], v[8:9], 2, v[6:7]
	v_add_u32_e32 v27, s23, v27
	v_lshl_add_u64 v[26:27], v[26:27], 2, v[6:7]
	global_load_dword v8, v[8:9], off
	s_nop 0
	global_load_dword v9, v[26:27], off
	v_or_b32_e32 v32, s22, v13
	v_mad_u64_u32 v[34:35], s[20:21], v32, s33, 0
	v_or_b32_e32 v32, s22, v14
	v_add_u32_e32 v35, s23, v35
	v_mad_u64_u32 v[36:37], s[20:21], v32, s33, 0
	v_lshl_add_u64 v[34:35], v[34:35], 2, v[6:7]
	v_add_u32_e32 v37, s23, v37
	v_or_b32_e32 v32, s22, v15
	v_lshl_add_u64 v[36:37], v[36:37], 2, v[6:7]
	global_load_dword v30, v[34:35], off
	global_load_dword v31, v[36:37], off
	v_mad_u64_u32 v[34:35], s[20:21], v32, s33, 0
	v_add_u32_e32 v32, s22, v16
	v_mad_u64_u32 v[36:37], s[20:21], v32, s33, 0
	v_ashrrev_i32_e32 v38, 31, v32
	v_mov_b32_e32 v32, v37
	v_mov_b32_e32 v33, 0
	v_add_u32_e32 v35, s23, v35
	v_mad_u64_u32 v[38:39], s[20:21], v38, s33, v[32:33]
	v_lshl_add_u64 v[34:35], v[34:35], 2, v[6:7]
	v_mov_b32_e32 v37, v38
	v_lshl_add_u64 v[42:43], v[36:37], 2, v[6:7]
	global_load_dword v40, v[34:35], off
	global_load_dword v41, v[42:43], off
	s_waitcnt vmcnt(7)
	v_mul_f32_e32 v4, s18, v4
	s_waitcnt vmcnt(6)
	v_mul_f32_e32 v26, s18, v28
	ds_write_b32 v21, v4
	ds_write_b32 v22, v26
	s_waitcnt vmcnt(4)
	v_pk_mul_f32 v[8:9], s[18:19], v[8:9] op_sel_hi:[0,1]

; __device__ void phase_prep(const Params& p, unsigned char* smem) {
;     ...
;         for (int e = 0; e < 8; ++e) { const int idx = e * 512 + tid, kk = idx >> 6, nn = idx & 63, n = n0 + nn;
;             t[kk * 65 + nn] = (n < N) ? src[(size_t)(k0 + kk) * N + n] * scale : 0.f; }
.LBB0_50:
	s_or_saveexec_b64 s[20:21], s[20:21]
	v_mov_b32_e32 v8, 0
	v_mov_b32_e32 v9, 0
	s_xor_b64 exec, exec, s[20:21]
	s_cbranch_execz .LBB0_23
	s_waitcnt vmcnt(3)
	v_mul_f32_e32 v4, s18, v30
	s_waitcnt vmcnt(2)
	v_mul_f32_e32 v6, s18, v31
	ds_write_b32 v21, v4 offset:8320
	ds_write_b32 v24, v6
	s_waitcnt vmcnt(0)
	v_pk_mul_f32 v[8:9], s[18:19], v[40:41] op_sel_hi:[0,1]
	s_branch .LBB0_23
